# v26 variant: V*KP product computed first as DPP-gap filler then fma with -sk*KKA (same f16 ops, one product rounded before the fma as before), operand reads at step start, R read and q write late with
# speedup vs baseline: 1.0152x; 1.0116x over previous
.LBB0_1238:
	s_or_b64 exec, exec, s[18:19]
	s_waitcnt lgkmcnt(0)
	s_barrier
	s_cmp_lg_u32 s100, 0
	s_cselect_b32 s97, 0x800, 0
	v_add_u32_e32 v167, s97, v114
	ds_read_b128 v[72:75], v114 offset:41216
	ds_read_b128 v[68:71], v114 offset:45312
	ds_read_b128 v[64:67], v114 offset:49408
	ds_read_b128 v[56:59], v114 offset:53504
	ds_read_b128 v[60:63], v167 offset:28928
	ds_read2st64_b32 v[214:215], v115 offset1:1
	s_waitcnt lgkmcnt(0)
	ds_read_b128 v[134:137], v114 offset:41344
	ds_read_b128 v[138:141], v114 offset:45440
	ds_read_b128 v[142:145], v114 offset:49536
	ds_read_b128 v[130:133], v167 offset:29056
	v_dot2_f32_f16 v151, v127, v72, 0
	v_dot2_f32_f16 v151, v126, v73, v151
	v_dot2_f32_f16 v151, v125, v74, v151
	v_dot2_f32_f16 v151, v124, v75, v151
	v_pk_mul_f16 v153, v214, v64
	v_pk_mul_f16 v154, v214, v65
	v_pk_mul_f16 v155, v214, v66
	v_add_f32_dpp v151, v151, v151 quad_perm:[1,0,3,2] row_mask:0xf bank_mask:0xf bound_ctrl:1
	v_pk_mul_f16 v156, v214, v67
	s_nop 0
	v_add_f32_dpp v151, v151, v151 quad_perm:[2,3,0,1] row_mask:0xf bank_mask:0xf bound_ctrl:1
	s_nop 1
	v_add_f32_dpp v151, v151, v151 row_half_mirror row_mask:0xf bank_mask:0xf bound_ctrl:1
	v_cvt_pkrtz_f16_f32 v152, -v151, -v151
	ds_read_b128 v[146:149], v114 offset:53632
	v_pk_fma_f16 v153, v152, v68, v153
	v_pk_fma_f16 v154, v152, v69, v154
	v_pk_fma_f16 v155, v152, v70, v155
	v_pk_fma_f16 v156, v152, v71, v156
	v_pk_fma_f16 v127, v127, v60, v153
	v_pk_fma_f16 v126, v126, v61, v154
	v_pk_fma_f16 v125, v125, v62, v155
	v_pk_fma_f16 v124, v124, v63, v156
	s_waitcnt lgkmcnt(1)
	ds_read_b128 v[72:75], v114 offset:41472
	ds_read_b128 v[68:71], v114 offset:45568
	ds_read_b128 v[64:67], v114 offset:49664
	ds_read_b128 v[60:63], v167 offset:29184
	ds_read2st64_b32 v[216:217], v115 offset0:2 offset1:3
	v_dot2_f32_f16 v151, v127, v134, 0
	v_dot2_f32_f16 v151, v126, v135, v151
	v_dot2_f32_f16 v151, v125, v136, v151
	v_dot2_f32_f16 v151, v124, v137, v151
	v_dot2_f32_f16 v157, v127, v56, 0
	v_dot2_f32_f16 v157, v126, v57, v157
	v_dot2_f32_f16 v157, v125, v58, v157
	v_add_f32_dpp v151, v151, v151 quad_perm:[1,0,3,2] row_mask:0xf bank_mask:0xf bound_ctrl:1
	v_dot2_f32_f16 v157, v124, v59, v157
	v_pk_mul_f16 v153, v215, v142
	v_add_f32_dpp v151, v151, v151 quad_perm:[2,3,0,1] row_mask:0xf bank_mask:0xf bound_ctrl:1
	v_pk_mul_f16 v154, v215, v143
	v_pk_mul_f16 v155, v215, v144
	v_pk_mul_f16 v156, v215, v145
	v_add_f32_dpp v151, v151, v151 row_half_mirror row_mask:0xf bank_mask:0xf bound_ctrl:1
	v_cvt_pkrtz_f16_f32 v152, -v151, -v151
	ds_read_b128 v[56:59], v114 offset:53760
	v_pk_fma_f16 v153, v152, v138, v153
	v_pk_fma_f16 v154, v152, v139, v154
	v_pk_fma_f16 v155, v152, v140, v155
	v_pk_fma_f16 v156, v152, v141, v156
	v_pk_fma_f16 v127, v127, v130, v153
	v_pk_fma_f16 v126, v126, v131, v154
	v_pk_fma_f16 v125, v125, v132, v155
	v_pk_fma_f16 v124, v124, v133, v156
	s_waitcnt lgkmcnt(1)
	ds_read_b128 v[134:137], v114 offset:41600
	ds_read_b128 v[138:141], v114 offset:45696
	ds_read_b128 v[142:145], v114 offset:49792
	ds_read_b128 v[130:133], v167 offset:29312
	v_dot2_f32_f16 v151, v127, v72, 0
	v_dot2_f32_f16 v151, v126, v73, v151
	v_dot2_f32_f16 v151, v125, v74, v151
	v_dot2_f32_f16 v151, v124, v75, v151
	v_dot2_f32_f16 v158, v127, v146, 0
	v_dot2_f32_f16 v158, v126, v147, v158
	v_dot2_f32_f16 v158, v125, v148, v158
	v_add_f32_dpp v151, v151, v151 quad_perm:[1,0,3,2] row_mask:0xf bank_mask:0xf bound_ctrl:1
	v_dot2_f32_f16 v158, v124, v149, v158
	v_pk_mul_f16 v153, v216, v64
	v_add_f32_dpp v151, v151, v151 quad_perm:[2,3,0,1] row_mask:0xf bank_mask:0xf bound_ctrl:1
	v_pk_mul_f16 v154, v216, v65
	v_pk_mul_f16 v155, v216, v66
	v_pk_mul_f16 v156, v216, v67
	v_add_f32_dpp v151, v151, v151 row_half_mirror row_mask:0xf bank_mask:0xf bound_ctrl:1
	v_cvt_pkrtz_f16_f32 v152, -v151, -v151
	ds_read_b128 v[146:149], v114 offset:53888
	ds_write2st64_b32 v116, v157, v158 offset0:0 offset1:8
	v_pk_fma_f16 v153, v152, v68, v153
	v_pk_fma_f16 v154, v152, v69, v154
	v_pk_fma_f16 v155, v152, v70, v155
	v_pk_fma_f16 v156, v152, v71, v156
	v_pk_fma_f16 v127, v127, v60, v153
	v_pk_fma_f16 v126, v126, v61, v154
	v_pk_fma_f16 v125, v125, v62, v155
	v_pk_fma_f16 v124, v124, v63, v156
	s_waitcnt lgkmcnt(2)
	ds_read_b128 v[72:75], v114 offset:41728
	ds_read_b128 v[68:71], v114 offset:45824
	ds_read_b128 v[64:67], v114 offset:49920
	ds_read_b128 v[60:63], v167 offset:29440
	ds_read2st64_b32 v[214:215], v115 offset0:4 offset1:5
	v_dot2_f32_f16 v151, v127, v134, 0
	v_dot2_f32_f16 v151, v126, v135, v151
	v_dot2_f32_f16 v151, v125, v136, v151
	v_dot2_f32_f16 v151, v124, v137, v151
	v_dot2_f32_f16 v157, v127, v56, 0
	v_dot2_f32_f16 v157, v126, v57, v157
	v_dot2_f32_f16 v157, v125, v58, v157
	v_add_f32_dpp v151, v151, v151 quad_perm:[1,0,3,2] row_mask:0xf bank_mask:0xf bound_ctrl:1
	v_dot2_f32_f16 v157, v124, v59, v157
	v_pk_mul_f16 v153, v217, v142
	v_add_f32_dpp v151, v151, v151 quad_perm:[2,3,0,1] row_mask:0xf bank_mask:0xf bound_ctrl:1
	v_pk_mul_f16 v154, v217, v143
	v_pk_mul_f16 v155, v217, v144
	v_pk_mul_f16 v156, v217, v145
	v_add_f32_dpp v151, v151, v151 row_half_mirror row_mask:0xf bank_mask:0xf bound_ctrl:1
	v_cvt_pkrtz_f16_f32 v152, -v151, -v151
	ds_read_b128 v[56:59], v114 offset:54016
	v_pk_fma_f16 v153, v152, v138, v153
	v_pk_fma_f16 v154, v152, v139, v154
	v_pk_fma_f16 v155, v152, v140, v155
	v_pk_fma_f16 v156, v152, v141, v156
	v_pk_fma_f16 v127, v127, v130, v153
	v_pk_fma_f16 v126, v126, v131, v154
	v_pk_fma_f16 v125, v125, v132, v155
	v_pk_fma_f16 v124, v124, v133, v156
	s_waitcnt lgkmcnt(1)
	ds_read_b128 v[134:137], v114 offset:41856
	ds_read_b128 v[138:141], v114 offset:45952
	ds_read_b128 v[142:145], v114 offset:50048
	ds_read_b128 v[130:133], v167 offset:29568
	v_dot2_f32_f16 v151, v127, v72, 0
	v_dot2_f32_f16 v151, v126, v73, v151
	v_dot2_f32_f16 v151, v125, v74, v151
	v_dot2_f32_f16 v151, v124, v75, v151
	v_dot2_f32_f16 v158, v127, v146, 0
	v_dot2_f32_f16 v158, v126, v147, v158
	v_dot2_f32_f16 v158, v125, v148, v158
	v_add_f32_dpp v151, v151, v151 quad_perm:[1,0,3,2] row_mask:0xf bank_mask:0xf bound_ctrl:1
	v_dot2_f32_f16 v158, v124, v149, v158
	v_pk_mul_f16 v153, v214, v64
	v_add_f32_dpp v151, v151, v151 quad_perm:[2,3,0,1] row_mask:0xf bank_mask:0xf bound_ctrl:1
	v_pk_mul_f16 v154, v214, v65
	v_pk_mul_f16 v155, v214, v66
	v_pk_mul_f16 v156, v214, v67
	v_add_f32_dpp v151, v151, v151 row_half_mirror row_mask:0xf bank_mask:0xf bound_ctrl:1
	v_cvt_pkrtz_f16_f32 v152, -v151, -v151
	ds_read_b128 v[146:149], v114 offset:54144
	ds_write2st64_b32 v116, v157, v158 offset0:16 offset1:24
	v_pk_fma_f16 v153, v152, v68, v153
	v_pk_fma_f16 v154, v152, v69, v154
	v_pk_fma_f16 v155, v152, v70, v155
	v_pk_fma_f16 v156, v152, v71, v156
	v_pk_fma_f16 v127, v127, v60, v153
	v_pk_fma_f16 v126, v126, v61, v154
	v_pk_fma_f16 v125, v125, v62, v155
	v_pk_fma_f16 v124, v124, v63, v156
	s_waitcnt lgkmcnt(2)
	ds_read_b128 v[72:75], v114 offset:41984
	ds_read_b128 v[68:71], v114 offset:46080
	ds_read_b128 v[64:67], v114 offset:50176
	ds_read_b128 v[60:63], v167 offset:29696
	ds_read2st64_b32 v[216:217], v115 offset0:6 offset1:7
	v_dot2_f32_f16 v151, v127, v134, 0
	v_dot2_f32_f16 v151, v126, v135, v151
	v_dot2_f32_f16 v151, v125, v136, v151
	v_dot2_f32_f16 v151, v124, v137, v151
	v_dot2_f32_f16 v157, v127, v56, 0
	v_dot2_f32_f16 v157, v126, v57, v157
	v_dot2_f32_f16 v157, v125, v58, v157
	v_add_f32_dpp v151, v151, v151 quad_perm:[1,0,3,2] row_mask:0xf bank_mask:0xf bound_ctrl:1
	v_dot2_f32_f16 v157, v124, v59, v157
	v_pk_mul_f16 v153, v215, v142
	v_add_f32_dpp v151, v151, v151 quad_perm:[2,3,0,1] row_mask:0xf bank_mask:0xf bound_ctrl:1
	v_pk_mul_f16 v154, v215, v143
	v_pk_mul_f16 v155, v215, v144
	v_pk_mul_f16 v156, v215, v145
	v_add_f32_dpp v151, v151, v151 row_half_mirror row_mask:0xf bank_mask:0xf bound_ctrl:1
	v_cvt_pkrtz_f16_f32 v152, -v151, -v151
	ds_read_b128 v[56:59], v114 offset:54272
	v_pk_fma_f16 v153, v152, v138, v153
	v_pk_fma_f16 v154, v152, v139, v154
	v_pk_fma_f16 v155, v152, v140, v155
	v_pk_fma_f16 v156, v152, v141, v156
	v_pk_fma_f16 v127, v127, v130, v153
	v_pk_fma_f16 v126, v126, v131, v154
	v_pk_fma_f16 v125, v125, v132, v155
	v_pk_fma_f16 v124, v124, v133, v156
	s_waitcnt lgkmcnt(1)
	ds_read_b128 v[134:137], v114 offset:42112
	ds_read_b128 v[138:141], v114 offset:46208
	ds_read_b128 v[142:145], v114 offset:50304
	ds_read_b128 v[130:133], v167 offset:29824
	v_dot2_f32_f16 v151, v127, v72, 0
	v_dot2_f32_f16 v151, v126, v73, v151
	v_dot2_f32_f16 v151, v125, v74, v151
	v_dot2_f32_f16 v151, v124, v75, v151
	v_dot2_f32_f16 v158, v127, v146, 0
	v_dot2_f32_f16 v158, v126, v147, v158
	v_dot2_f32_f16 v158, v125, v148, v158
	v_add_f32_dpp v151, v151, v151 quad_perm:[1,0,3,2] row_mask:0xf bank_mask:0xf bound_ctrl:1
	v_dot2_f32_f16 v158, v124, v149, v158
	v_pk_mul_f16 v153, v216, v64
	v_add_f32_dpp v151, v151, v151 quad_perm:[2,3,0,1] row_mask:0xf bank_mask:0xf bound_ctrl:1
	v_pk_mul_f16 v154, v216, v65
	v_pk_mul_f16 v155, v216, v66
	v_pk_mul_f16 v156, v216, v67
	v_add_f32_dpp v151, v151, v151 row_half_mirror row_mask:0xf bank_mask:0xf bound_ctrl:1
	v_cvt_pkrtz_f16_f32 v152, -v151, -v151
	ds_read_b128 v[146:149], v114 offset:54400
	ds_write2st64_b32 v116, v157, v158 offset0:32 offset1:40
	v_pk_fma_f16 v153, v152, v68, v153
	v_pk_fma_f16 v154, v152, v69, v154
	v_pk_fma_f16 v155, v152, v70, v155
	v_pk_fma_f16 v156, v152, v71, v156
	v_pk_fma_f16 v127, v127, v60, v153
	v_pk_fma_f16 v126, v126, v61, v154
	v_pk_fma_f16 v125, v125, v62, v155
	v_pk_fma_f16 v124, v124, v63, v156
	s_waitcnt lgkmcnt(2)
	ds_read_b128 v[72:75], v114 offset:42240
	ds_read_b128 v[68:71], v114 offset:46336
	ds_read_b128 v[64:67], v114 offset:50432
	ds_read_b128 v[60:63], v167 offset:29952
	ds_read2st64_b32 v[214:215], v115 offset0:8 offset1:9
	v_dot2_f32_f16 v151, v127, v134, 0
	v_dot2_f32_f16 v151, v126, v135, v151
	v_dot2_f32_f16 v151, v125, v136, v151
	v_dot2_f32_f16 v151, v124, v137, v151
	v_dot2_f32_f16 v157, v127, v56, 0
	v_dot2_f32_f16 v157, v126, v57, v157
	v_dot2_f32_f16 v157, v125, v58, v157
	v_add_f32_dpp v151, v151, v151 quad_perm:[1,0,3,2] row_mask:0xf bank_mask:0xf bound_ctrl:1
	v_dot2_f32_f16 v157, v124, v59, v157
	v_pk_mul_f16 v153, v217, v142
	v_add_f32_dpp v151, v151, v151 quad_perm:[2,3,0,1] row_mask:0xf bank_mask:0xf bound_ctrl:1
	v_pk_mul_f16 v154, v217, v143
	v_pk_mul_f16 v155, v217, v144
	v_pk_mul_f16 v156, v217, v145
	v_add_f32_dpp v151, v151, v151 row_half_mirror row_mask:0xf bank_mask:0xf bound_ctrl:1
	v_cvt_pkrtz_f16_f32 v152, -v151, -v151
	ds_read_b128 v[56:59], v114 offset:54528
	v_pk_fma_f16 v153, v152, v138, v153
	v_pk_fma_f16 v154, v152, v139, v154
	v_pk_fma_f16 v155, v152, v140, v155
	v_pk_fma_f16 v156, v152, v141, v156
	v_pk_fma_f16 v127, v127, v130, v153
	v_pk_fma_f16 v126, v126, v131, v154
	v_pk_fma_f16 v125, v125, v132, v155
	v_pk_fma_f16 v124, v124, v133, v156
	s_waitcnt lgkmcnt(1)
	ds_read_b128 v[134:137], v114 offset:42368
	ds_read_b128 v[138:141], v114 offset:46464
	ds_read_b128 v[142:145], v114 offset:50560
	ds_read_b128 v[130:133], v167 offset:30080
	v_dot2_f32_f16 v151, v127, v72, 0
	v_dot2_f32_f16 v151, v126, v73, v151
	v_dot2_f32_f16 v151, v125, v74, v151
	v_dot2_f32_f16 v151, v124, v75, v151
	v_dot2_f32_f16 v158, v127, v146, 0
	v_dot2_f32_f16 v158, v126, v147, v158
	v_dot2_f32_f16 v158, v125, v148, v158
	v_add_f32_dpp v151, v151, v151 quad_perm:[1,0,3,2] row_mask:0xf bank_mask:0xf bound_ctrl:1
	v_dot2_f32_f16 v158, v124, v149, v158
	v_pk_mul_f16 v153, v214, v64
	v_add_f32_dpp v151, v151, v151 quad_perm:[2,3,0,1] row_mask:0xf bank_mask:0xf bound_ctrl:1
	v_pk_mul_f16 v154, v214, v65
	v_pk_mul_f16 v155, v214, v66
	v_pk_mul_f16 v156, v214, v67
	v_add_f32_dpp v151, v151, v151 row_half_mirror row_mask:0xf bank_mask:0xf bound_ctrl:1
	v_cvt_pkrtz_f16_f32 v152, -v151, -v151
	ds_read_b128 v[146:149], v114 offset:54656
	ds_write2st64_b32 v116, v157, v158 offset0:48 offset1:56
	v_pk_fma_f16 v153, v152, v68, v153
	v_pk_fma_f16 v154, v152, v69, v154
	v_pk_fma_f16 v155, v152, v70, v155
	v_pk_fma_f16 v156, v152, v71, v156
	v_pk_fma_f16 v127, v127, v60, v153
	v_pk_fma_f16 v126, v126, v61, v154
	v_pk_fma_f16 v125, v125, v62, v155
	v_pk_fma_f16 v124, v124, v63, v156
	s_waitcnt lgkmcnt(2)
	ds_read_b128 v[72:75], v114 offset:42496
	ds_read_b128 v[68:71], v114 offset:46592
	ds_read_b128 v[64:67], v114 offset:50688
	ds_read_b128 v[60:63], v167 offset:30208
	ds_read2st64_b32 v[216:217], v115 offset0:10 offset1:11
	v_dot2_f32_f16 v151, v127, v134, 0
	v_dot2_f32_f16 v151, v126, v135, v151
	v_dot2_f32_f16 v151, v125, v136, v151
	v_dot2_f32_f16 v151, v124, v137, v151
	v_dot2_f32_f16 v157, v127, v56, 0
	v_dot2_f32_f16 v157, v126, v57, v157
	v_dot2_f32_f16 v157, v125, v58, v157
	v_add_f32_dpp v151, v151, v151 quad_perm:[1,0,3,2] row_mask:0xf bank_mask:0xf bound_ctrl:1
	v_dot2_f32_f16 v157, v124, v59, v157
	v_pk_mul_f16 v153, v215, v142
	v_add_f32_dpp v151, v151, v151 quad_perm:[2,3,0,1] row_mask:0xf bank_mask:0xf bound_ctrl:1
	v_pk_mul_f16 v154, v215, v143
	v_pk_mul_f16 v155, v215, v144
	v_pk_mul_f16 v156, v215, v145
	v_add_f32_dpp v151, v151, v151 row_half_mirror row_mask:0xf bank_mask:0xf bound_ctrl:1
	v_cvt_pkrtz_f16_f32 v152, -v151, -v151
	ds_read_b128 v[56:59], v114 offset:54784
	v_pk_fma_f16 v153, v152, v138, v153
	v_pk_fma_f16 v154, v152, v139, v154
	v_pk_fma_f16 v155, v152, v140, v155
	v_pk_fma_f16 v156, v152, v141, v156
	v_pk_fma_f16 v127, v127, v130, v153
	v_pk_fma_f16 v126, v126, v131, v154
	v_pk_fma_f16 v125, v125, v132, v155
	v_pk_fma_f16 v124, v124, v133, v156
	s_waitcnt lgkmcnt(1)
	ds_read_b128 v[134:137], v114 offset:42624
	ds_read_b128 v[138:141], v114 offset:46720
	ds_read_b128 v[142:145], v114 offset:50816
	ds_read_b128 v[130:133], v167 offset:30336
	v_dot2_f32_f16 v151, v127, v72, 0
	v_dot2_f32_f16 v151, v126, v73, v151
	v_dot2_f32_f16 v151, v125, v74, v151
	v_dot2_f32_f16 v151, v124, v75, v151
	v_dot2_f32_f16 v158, v127, v146, 0
	v_dot2_f32_f16 v158, v126, v147, v158
	v_dot2_f32_f16 v158, v125, v148, v158
	v_add_f32_dpp v151, v151, v151 quad_perm:[1,0,3,2] row_mask:0xf bank_mask:0xf bound_ctrl:1
	v_dot2_f32_f16 v158, v124, v149, v158
	v_pk_mul_f16 v153, v216, v64
	v_add_f32_dpp v151, v151, v151 quad_perm:[2,3,0,1] row_mask:0xf bank_mask:0xf bound_ctrl:1
	v_pk_mul_f16 v154, v216, v65
	v_pk_mul_f16 v155, v216, v66
	v_pk_mul_f16 v156, v216, v67
	v_add_f32_dpp v151, v151, v151 row_half_mirror row_mask:0xf bank_mask:0xf bound_ctrl:1
	v_cvt_pkrtz_f16_f32 v152, -v151, -v151
	ds_read_b128 v[146:149], v114 offset:54912
	ds_write2st64_b32 v116, v157, v158 offset0:64 offset1:72
	v_pk_fma_f16 v153, v152, v68, v153
	v_pk_fma_f16 v154, v152, v69, v154
	v_pk_fma_f16 v155, v152, v70, v155
	v_pk_fma_f16 v156, v152, v71, v156
	v_pk_fma_f16 v127, v127, v60, v153
	v_pk_fma_f16 v126, v126, v61, v154
	v_pk_fma_f16 v125, v125, v62, v155
	v_pk_fma_f16 v124, v124, v63, v156
	s_waitcnt lgkmcnt(2)
	ds_read_b128 v[72:75], v114 offset:42752
	ds_read_b128 v[68:71], v114 offset:46848
	ds_read_b128 v[64:67], v114 offset:50944
	ds_read_b128 v[60:63], v167 offset:30464
	ds_read2st64_b32 v[214:215], v115 offset0:12 offset1:13
	v_dot2_f32_f16 v151, v127, v134, 0
	v_dot2_f32_f16 v151, v126, v135, v151
	v_dot2_f32_f16 v151, v125, v136, v151
	v_dot2_f32_f16 v151, v124, v137, v151
	v_dot2_f32_f16 v157, v127, v56, 0
	v_dot2_f32_f16 v157, v126, v57, v157
	v_dot2_f32_f16 v157, v125, v58, v157
	v_add_f32_dpp v151, v151, v151 quad_perm:[1,0,3,2] row_mask:0xf bank_mask:0xf bound_ctrl:1
	v_dot2_f32_f16 v157, v124, v59, v157
	v_pk_mul_f16 v153, v217, v142
	v_add_f32_dpp v151, v151, v151 quad_perm:[2,3,0,1] row_mask:0xf bank_mask:0xf bound_ctrl:1
	v_pk_mul_f16 v154, v217, v143
	v_pk_mul_f16 v155, v217, v144
	v_pk_mul_f16 v156, v217, v145
	v_add_f32_dpp v151, v151, v151 row_half_mirror row_mask:0xf bank_mask:0xf bound_ctrl:1
	v_cvt_pkrtz_f16_f32 v152, -v151, -v151
	ds_read_b128 v[56:59], v114 offset:55040
	v_pk_fma_f16 v153, v152, v138, v153
	v_pk_fma_f16 v154, v152, v139, v154
	v_pk_fma_f16 v155, v152, v140, v155
	v_pk_fma_f16 v156, v152, v141, v156
	v_pk_fma_f16 v127, v127, v130, v153
	v_pk_fma_f16 v126, v126, v131, v154
	v_pk_fma_f16 v125, v125, v132, v155
	v_pk_fma_f16 v124, v124, v133, v156
	s_waitcnt lgkmcnt(1)
	ds_read_b128 v[134:137], v114 offset:42880
	ds_read_b128 v[138:141], v114 offset:46976
	ds_read_b128 v[142:145], v114 offset:51072
	ds_read_b128 v[130:133], v167 offset:30592
	v_dot2_f32_f16 v151, v127, v72, 0
	v_dot2_f32_f16 v151, v126, v73, v151
	v_dot2_f32_f16 v151, v125, v74, v151
	v_dot2_f32_f16 v151, v124, v75, v151
	v_dot2_f32_f16 v158, v127, v146, 0
	v_dot2_f32_f16 v158, v126, v147, v158
	v_dot2_f32_f16 v158, v125, v148, v158
	v_add_f32_dpp v151, v151, v151 quad_perm:[1,0,3,2] row_mask:0xf bank_mask:0xf bound_ctrl:1
	v_dot2_f32_f16 v158, v124, v149, v158
	v_pk_mul_f16 v153, v214, v64
	v_add_f32_dpp v151, v151, v151 quad_perm:[2,3,0,1] row_mask:0xf bank_mask:0xf bound_ctrl:1
	v_pk_mul_f16 v154, v214, v65
	v_pk_mul_f16 v155, v214, v66
	v_pk_mul_f16 v156, v214, v67
	v_add_f32_dpp v151, v151, v151 row_half_mirror row_mask:0xf bank_mask:0xf bound_ctrl:1
	v_cvt_pkrtz_f16_f32 v152, -v151, -v151
	ds_read_b128 v[146:149], v114 offset:55168
	ds_write2st64_b32 v116, v157, v158 offset0:80 offset1:88
	v_pk_fma_f16 v153, v152, v68, v153
	v_pk_fma_f16 v154, v152, v69, v154
	v_pk_fma_f16 v155, v152, v70, v155
	v_pk_fma_f16 v156, v152, v71, v156
	v_pk_fma_f16 v127, v127, v60, v153
	v_pk_fma_f16 v126, v126, v61, v154
	v_pk_fma_f16 v125, v125, v62, v155
	v_pk_fma_f16 v124, v124, v63, v156
	s_waitcnt lgkmcnt(2)
	ds_read_b128 v[72:75], v114 offset:43008
	ds_read_b128 v[68:71], v114 offset:47104
	ds_read_b128 v[64:67], v114 offset:51200
	ds_read_b128 v[60:63], v167 offset:30720
	ds_read2st64_b32 v[216:217], v115 offset0:14 offset1:15
	v_dot2_f32_f16 v151, v127, v134, 0
	v_dot2_f32_f16 v151, v126, v135, v151
	v_dot2_f32_f16 v151, v125, v136, v151
	v_dot2_f32_f16 v151, v124, v137, v151
	v_dot2_f32_f16 v157, v127, v56, 0
	v_dot2_f32_f16 v157, v126, v57, v157
	v_dot2_f32_f16 v157, v125, v58, v157
	v_add_f32_dpp v151, v151, v151 quad_perm:[1,0,3,2] row_mask:0xf bank_mask:0xf bound_ctrl:1
	v_dot2_f32_f16 v157, v124, v59, v157
	v_pk_mul_f16 v153, v215, v142
	v_add_f32_dpp v151, v151, v151 quad_perm:[2,3,0,1] row_mask:0xf bank_mask:0xf bound_ctrl:1
	v_pk_mul_f16 v154, v215, v143
	v_pk_mul_f16 v155, v215, v144
	v_pk_mul_f16 v156, v215, v145
	v_add_f32_dpp v151, v151, v151 row_half_mirror row_mask:0xf bank_mask:0xf bound_ctrl:1
	v_cvt_pkrtz_f16_f32 v152, -v151, -v151
	ds_read_b128 v[56:59], v114 offset:55296
	v_pk_fma_f16 v153, v152, v138, v153
	v_pk_fma_f16 v154, v152, v139, v154
	v_pk_fma_f16 v155, v152, v140, v155
	v_pk_fma_f16 v156, v152, v141, v156
	v_pk_fma_f16 v127, v127, v130, v153
	v_pk_fma_f16 v126, v126, v131, v154
	v_pk_fma_f16 v125, v125, v132, v155
	v_pk_fma_f16 v124, v124, v133, v156
	s_waitcnt lgkmcnt(1)
	ds_read_b128 v[134:137], v114 offset:43136
	ds_read_b128 v[138:141], v114 offset:47232
	ds_read_b128 v[142:145], v114 offset:51328
	ds_read_b128 v[130:133], v167 offset:30848
	v_dot2_f32_f16 v151, v127, v72, 0
	v_dot2_f32_f16 v151, v126, v73, v151
	v_dot2_f32_f16 v151, v125, v74, v151
	v_dot2_f32_f16 v151, v124, v75, v151
	v_dot2_f32_f16 v158, v127, v146, 0
	v_dot2_f32_f16 v158, v126, v147, v158
	v_dot2_f32_f16 v158, v125, v148, v158
	v_add_f32_dpp v151, v151, v151 quad_perm:[1,0,3,2] row_mask:0xf bank_mask:0xf bound_ctrl:1
	v_dot2_f32_f16 v158, v124, v149, v158
	v_pk_mul_f16 v153, v216, v64
	v_add_f32_dpp v151, v151, v151 quad_perm:[2,3,0,1] row_mask:0xf bank_mask:0xf bound_ctrl:1
	v_pk_mul_f16 v154, v216, v65
	v_pk_mul_f16 v155, v216, v66
	v_pk_mul_f16 v156, v216, v67
	v_add_f32_dpp v151, v151, v151 row_half_mirror row_mask:0xf bank_mask:0xf bound_ctrl:1
	v_cvt_pkrtz_f16_f32 v152, -v151, -v151
	ds_read_b128 v[146:149], v114 offset:55424
	ds_write2st64_b32 v116, v157, v158 offset0:96 offset1:104
	v_pk_fma_f16 v153, v152, v68, v153
	v_pk_fma_f16 v154, v152, v69, v154
	v_pk_fma_f16 v155, v152, v70, v155
	v_pk_fma_f16 v156, v152, v71, v156
	v_pk_fma_f16 v127, v127, v60, v153
	v_pk_fma_f16 v126, v126, v61, v154
	v_pk_fma_f16 v125, v125, v62, v155
	v_pk_fma_f16 v124, v124, v63, v156
	s_waitcnt lgkmcnt(0)
	v_dot2_f32_f16 v151, v127, v134, 0
	v_dot2_f32_f16 v151, v126, v135, v151
	v_dot2_f32_f16 v151, v125, v136, v151
	v_dot2_f32_f16 v151, v124, v137, v151
	v_dot2_f32_f16 v157, v127, v56, 0
	v_dot2_f32_f16 v157, v126, v57, v157
	v_dot2_f32_f16 v157, v125, v58, v157
	v_add_f32_dpp v151, v151, v151 quad_perm:[1,0,3,2] row_mask:0xf bank_mask:0xf bound_ctrl:1
	v_dot2_f32_f16 v157, v124, v59, v157
	v_pk_mul_f16 v153, v217, v142
	v_add_f32_dpp v151, v151, v151 quad_perm:[2,3,0,1] row_mask:0xf bank_mask:0xf bound_ctrl:1
	v_pk_mul_f16 v154, v217, v143
	v_pk_mul_f16 v155, v217, v144
	v_pk_mul_f16 v156, v217, v145
	v_add_f32_dpp v151, v151, v151 row_half_mirror row_mask:0xf bank_mask:0xf bound_ctrl:1
	v_cvt_pkrtz_f16_f32 v152, -v151, -v151
	v_pk_fma_f16 v153, v152, v138, v153
	v_pk_fma_f16 v154, v152, v139, v154
	v_pk_fma_f16 v155, v152, v140, v155
	v_pk_fma_f16 v156, v152, v141, v156
	v_pk_fma_f16 v127, v127, v130, v153
	v_pk_fma_f16 v126, v126, v131, v154
	v_pk_fma_f16 v125, v125, v132, v155
	v_pk_fma_f16 v124, v124, v133, v156
	v_dot2_f32_f16 v158, v127, v146, 0
	v_dot2_f32_f16 v158, v126, v147, v158
	v_dot2_f32_f16 v158, v125, v148, v158
	v_dot2_f32_f16 v158, v124, v149, v158
	s_nop 2
	ds_write2st64_b32 v116, v157, v158 offset0:112 offset1:120
	s_xor_b32 s100, s100, 0xe100
	s_cmpk_lg_i32 s30, 0x80
	s_cbranch_scc0 .LBB0_1250
	s_mov_b32 s4, s30
	s_and_saveexec_b64 s[18:19], s[10:11]
	s_cbranch_execnz .LBB0_1229
	s_branch .LBB0_1230
